# GEMM unit header: store-drain wait moved after the accumulator zeroing; in-proj stagger sleep moved after the prologue's tile loads
# speedup vs baseline: 1.0049x; 1.0009x over previous
.LBB0_447:
	s_andn2_b64 vcc, exec, s[0:1]
	s_cbranch_vccnz .LBB0_584
	s_mov_b64 s[4:5], s[40:41]
	s_mov_b64 s[6:7], s[40:41]
	s_mov_b64 s[36:37], s[40:41]
	s_mov_b64 s[38:39], s[40:41]
	s_mov_b64 s[0:1], s[40:41]
	s_mov_b32 s26, -1
	s_nop 0
	v_mbcnt_lo_u32_b32 v0, s26, 0
	v_mbcnt_hi_u32_b32 v0, s26, v0
	v_readlane_b32 s26, v252, 5
	s_nop 1
	v_add_u32_e32 v8, s26, v0
	v_readlane_b32 s26, v252, 9
	v_readlane_b32 s27, v252, 10
	s_andn2_b64 vcc, exec, s[26:27]
	v_readfirstlane_b32 s26, v8
	s_cbranch_vccnz .LBB0_528
	v_lshlrev_b32_e32 v0, 4, v8
	s_waitcnt lgkmcnt(0)
	v_add_u32_e32 v1, 0x2000, v0
	v_ashrrev_i32_e32 v2, 31, v1
	v_lshrrev_b32_e32 v2, 22, v2
	v_add_u32_e32 v2, v1, v2
	v_ashrrev_i32_e32 v9, 10, v2
	v_mul_i32_i24_e32 v2, 0x400, v9
	v_sub_u32_e32 v1, v1, v2
	v_lshrrev_b32_e32 v2, 4, v1
	v_bitop3_b32 v1, v2, v1, 32 bitop3:0x6c
	v_readlane_b32 s28, v254, 43
	v_ashrrev_i32_e32 v2, 31, v1
	v_readlane_b32 s29, v254, 44
	s_add_u32 s58, s4, 0x13600000
	v_lshrrev_b32_e32 v2, 26, v2
	s_addc_u32 s59, s5, 0
	s_mov_b32 s5, s29
	v_add_u32_e32 v2, v1, v2
	v_lshlrev_b32_e32 v3, 3, v9
	s_mul_i32 s28, s96, 0x2c0000
	v_writelane_b32 v254, s4, 43
	v_ashrrev_i32_e32 v10, 6, v2
	v_and_b32_e32 v3, -16, v3
	v_writelane_b32 v254, s5, 44
	s_lshl_b64 s[4:5], s[28:29], 1
	v_add_u32_e32 v3, v10, v3
	s_add_u32 s34, s6, s4
	v_and_b32_e32 v4, 3, v10
	s_mov_b32 s4, 0x1fffe0
	v_lshrrev_b32_e32 v5, 2, v3
	v_lshlrev_b32_e32 v6, 1, v3
	v_and_or_b32 v4, v3, s4, v4
	v_and_b32_e32 v5, 4, v5
	v_and_b32_e32 v6, 24, v6
	v_and_b32_e32 v2, 0xc0, v2
	v_or3_b32 v4, v4, v5, v6
	v_sub_u32_e32 v1, v1, v2
	v_mov_b32_e32 v6, 1
	v_lshlrev_b32_e32 v5, 5, v9
	v_ashrrev_i16_sdwa v1, v6, sext(v1) dst_sel:DWORD dst_unused:UNUSED_PAD src0_sel:DWORD src1_sel:BYTE_0
	v_and_b32_e32 v5, 32, v5
	v_bfe_i32 v11, v1, 0, 16
	v_add_lshl_u32 v1, v5, v11, 1
	v_lshl_add_u32 v130, v4, 11, v1
	v_lshl_add_u32 v132, v3, 11, v1
	v_bfe_i32 v1, v8, 27, 1
	v_lshrrev_b32_e32 v1, 22, v1
	v_add_u32_e32 v1, v0, v1
	v_and_b32_e32 v1, 0xfffffc00, v1
	v_sub_u32_e32 v0, v0, v1
	v_lshrrev_b32_e32 v1, 4, v0
	v_ashrrev_i32_e32 v2, 31, v8
	v_bitop3_b32 v0, v1, v0, 32 bitop3:0x6c
	v_lshrrev_b32_e32 v2, 26, v2
	v_ashrrev_i32_e32 v1, 31, v0
	v_add_u32_e32 v2, v8, v2
	v_lshrrev_b32_e32 v1, 26, v1
	v_ashrrev_i32_e32 v13, 6, v2
	v_add_u32_e32 v1, v0, v1
	v_lshlrev_b32_e32 v2, 3, v13
	v_ashrrev_i32_e32 v12, 6, v1
	v_and_b32_e32 v2, -16, v2
	v_add_u32_e32 v2, v12, v2
	v_and_b32_e32 v3, 3, v12
	v_lshrrev_b32_e32 v4, 2, v2
	v_lshlrev_b32_e32 v5, 1, v2
	v_and_b32_e32 v1, 0xc0, v1
	s_addc_u32 s60, s7, s5
	s_ashr_i32 s28, s26, 6
	v_and_or_b32 v3, v2, s4, v3
	v_and_b32_e32 v4, 4, v4
	v_and_b32_e32 v5, 24, v5
	v_sub_u32_e32 v0, v0, v1
	s_ashr_i32 s27, s26, 8
	s_lshl_b32 s61, s28, 10
	v_or3_b32 v3, v3, v4, v5
	v_lshlrev_b32_e32 v4, 5, v13
	v_ashrrev_i16_sdwa v0, v6, sext(v0) dst_sel:DWORD dst_unused:UNUSED_PAD src0_sel:DWORD src1_sel:BYTE_0
	v_readlane_b32 s4, v253, 46
	v_and_b32_e32 v4, 32, v4
	v_bfe_i32 v14, v0, 0, 16
	v_readlane_b32 s5, v253, 47
	s_add_u32 s4, s34, s4
	v_add_lshl_u32 v0, v4, v14, 1
	s_addc_u32 s5, s60, s5
	s_add_i32 s62, s61, 0
	v_lshl_add_u32 v64, v3, 11, v0
	s_add_i32 m0, s62, 0x10000
	v_lshl_add_u32 v134, v2, 11, v0
	global_load_lds_dwordx4 v64, s[4:5]
	s_add_i32 m0, s62, 0x12000
	s_add_u32 s6, s4, 0x40000
	global_load_lds_dwordx4 v130, s[4:5]
	s_addc_u32 s7, s5, 0
	s_add_i32 m0, s62, 0x14000
	v_mov_b32_e32 v131, v65
	global_load_lds_dwordx4 v64, s[6:7]
	s_add_i32 m0, s62, 0x16000
	v_mov_b32_e32 v135, v65
	global_load_lds_dwordx4 v130, s[6:7]
	v_readlane_b32 s6, v253, 57
	v_readlane_b32 s7, v253, 58
	s_add_u32 s30, s58, s6
	s_addc_u32 s31, s59, s7
	s_add_i32 s63, s62, 0x2000
	s_mov_b32 m0, s62
	s_add_u32 s6, s30, 0x40000
	global_load_lds_dwordx4 v134, s[30:31]
	s_mov_b32 m0, s63
	s_addc_u32 s7, s31, 0
	s_add_i32 s64, s62, 0x4000
	global_load_lds_dwordx4 v132, s[30:31]
	s_mov_b32 m0, s64
	s_add_i32 s65, s62, 0x6000
	global_load_lds_dwordx4 v134, s[6:7]
	s_mov_b32 m0, s65
	v_mov_b32_e32 v133, v65
	global_load_lds_dwordx4 v132, s[6:7]
	v_readlane_b32 s46, v252, 0
	s_nop 1
	s_lshr_b32 s46, s46, 6
	s_cmp_eq_u32 s46, 0
	s_cbranch_scc1 .LstagA_done
.LstagA_loop:
	s_sleep 64
	s_sub_u32 s46, s46, 1
	s_cmp_lg_u32 s46, 0
	s_cbranch_scc1 .LstagA_loop
.LstagA_done:
	s_cmp_eq_u32 s27, 1
	v_lshl_add_u64 v[6:7], s[4:5], 0, v[64:65]
	v_lshl_add_u64 v[4:5], s[4:5], 0, v[130:131]
	v_lshl_add_u64 v[0:1], s[30:31], 0, v[134:135]
	s_cselect_b64 s[6:7], -1, 0
	s_cmp_lg_u32 s27, 1
	v_lshl_add_u64 v[2:3], s[30:31], 0, v[132:133]
	s_cbranch_scc1 .LBB0_451
	s_barrier

.LBB0_456:
	s_ashr_i32 s49, s48, 31
	s_lshl_b64 s[28:29], s[48:49], 19
	s_add_u32 s50, s58, s28
	s_addc_u32 s51, s59, s29
	s_and_b64 s[28:29], s[0:1], exec
	s_cselect_b32 s28, s51, s31
	s_cselect_b32 s29, s50, s30
	s_ashr_i32 s47, s46, 31
	s_lshl_b64 s[52:53], s[46:47], 19
	s_add_u32 s52, s34, s52
	s_addc_u32 s53, s60, s53
	s_and_b64 s[54:55], s[0:1], exec
	s_cselect_b32 s33, s53, s5
	s_cselect_b32 s35, s52, s4
	s_add_u32 s47, s4, 0x100
	s_addc_u32 s49, s5, 0
	s_add_u32 s4, s30, 0x40080
	v_mov_b32_e32 v0, 0
	s_addc_u32 s5, s31, 0
	s_mov_b32 s56, -2
	v_mov_b32_e32 v1, v0
	v_mov_b32_e32 v2, v0
	v_mov_b32_e32 v3, v0
	v_mov_b32_e32 v4, v0
	v_mov_b32_e32 v5, v0
	v_mov_b32_e32 v6, v0
	v_mov_b32_e32 v7, v0
	v_mov_b32_e32 v16, v0
	v_mov_b32_e32 v17, v0
	v_mov_b32_e32 v18, v0
	v_mov_b32_e32 v19, v0
	v_mov_b32_e32 v20, v0
	v_mov_b32_e32 v21, v0
	v_mov_b32_e32 v22, v0
	v_mov_b32_e32 v23, v0
	v_mov_b32_e32 v32, v0
	v_mov_b32_e32 v33, v0
	v_mov_b32_e32 v34, v0
	v_mov_b32_e32 v35, v0
	v_mov_b32_e32 v36, v0
	v_mov_b32_e32 v37, v0
	v_mov_b32_e32 v38, v0
	v_mov_b32_e32 v39, v0
	v_mov_b32_e32 v48, v0
	v_mov_b32_e32 v49, v0
	v_mov_b32_e32 v50, v0
	v_mov_b32_e32 v51, v0
	v_mov_b32_e32 v52, v0
	v_mov_b32_e32 v53, v0
	v_mov_b32_e32 v54, v0
	v_mov_b32_e32 v55, v0
	v_mov_b32_e32 v8, v0
	v_mov_b32_e32 v9, v0
	v_mov_b32_e32 v10, v0
	v_mov_b32_e32 v11, v0
	v_mov_b32_e32 v12, v0
	v_mov_b32_e32 v13, v0
	v_mov_b32_e32 v14, v0
	v_mov_b32_e32 v15, v0
	v_mov_b32_e32 v24, v0
	v_mov_b32_e32 v25, v0
	v_mov_b32_e32 v26, v0
	v_mov_b32_e32 v27, v0
	v_mov_b32_e32 v28, v0
	v_mov_b32_e32 v29, v0
	v_mov_b32_e32 v30, v0
	v_mov_b32_e32 v31, v0
	v_mov_b32_e32 v40, v0
	v_mov_b32_e32 v41, v0
	v_mov_b32_e32 v42, v0
	v_mov_b32_e32 v43, v0
	v_mov_b32_e32 v44, v0
	v_mov_b32_e32 v45, v0
	v_mov_b32_e32 v46, v0
	v_mov_b32_e32 v47, v0
	v_mov_b32_e32 v56, v0
	v_mov_b32_e32 v57, v0
	v_mov_b32_e32 v58, v0
	v_mov_b32_e32 v59, v0
	v_mov_b32_e32 v60, v0
	v_mov_b32_e32 v61, v0
	v_mov_b32_e32 v62, v0
	v_mov_b32_e32 v63, v0
	v_mov_b32_e32 v66, v0
	v_mov_b32_e32 v67, v0
	v_mov_b32_e32 v68, v0
	v_mov_b32_e32 v69, v0
	v_mov_b32_e32 v70, v0
	v_mov_b32_e32 v71, v0
	v_mov_b32_e32 v72, v0
	v_mov_b32_e32 v73, v0
	v_mov_b32_e32 v82, v0
	v_mov_b32_e32 v83, v0
	v_mov_b32_e32 v84, v0
	v_mov_b32_e32 v85, v0
	v_mov_b32_e32 v86, v0
	v_mov_b32_e32 v87, v0
	v_mov_b32_e32 v88, v0
	v_mov_b32_e32 v89, v0
	v_mov_b32_e32 v98, v0
	v_mov_b32_e32 v99, v0
	v_mov_b32_e32 v100, v0
	v_mov_b32_e32 v101, v0
	v_mov_b32_e32 v102, v0
	v_mov_b32_e32 v103, v0
	v_mov_b32_e32 v104, v0
	v_mov_b32_e32 v105, v0
	v_mov_b32_e32 v114, v0
	v_mov_b32_e32 v115, v0
	v_mov_b32_e32 v116, v0
	v_mov_b32_e32 v117, v0
	v_mov_b32_e32 v118, v0
	v_mov_b32_e32 v119, v0
	v_mov_b32_e32 v120, v0
	v_mov_b32_e32 v121, v0
	v_mov_b32_e32 v74, v0
	v_mov_b32_e32 v75, v0
	v_mov_b32_e32 v76, v0
	v_mov_b32_e32 v77, v0
	v_mov_b32_e32 v78, v0
	v_mov_b32_e32 v79, v0
	v_mov_b32_e32 v80, v0
	v_mov_b32_e32 v81, v0
	v_mov_b32_e32 v90, v0
	v_mov_b32_e32 v91, v0
	v_mov_b32_e32 v92, v0
	v_mov_b32_e32 v93, v0
	v_mov_b32_e32 v94, v0
	v_mov_b32_e32 v95, v0
	v_mov_b32_e32 v96, v0
	v_mov_b32_e32 v97, v0
	v_mov_b32_e32 v106, v0
	v_mov_b32_e32 v107, v0
	v_mov_b32_e32 v108, v0
	v_mov_b32_e32 v109, v0
	v_mov_b32_e32 v110, v0
	v_mov_b32_e32 v111, v0
	v_mov_b32_e32 v112, v0
	v_mov_b32_e32 v113, v0
	v_mov_b32_e32 v122, v0
	v_mov_b32_e32 v123, v0
	v_mov_b32_e32 v124, v0
	v_mov_b32_e32 v125, v0
	v_mov_b32_e32 v126, v0
	v_mov_b32_e32 v127, v0
	v_mov_b32_e32 v128, v0
	v_mov_b32_e32 v129, v0
	s_waitcnt vmcnt(0)

.LBB0_1160:
	s_ashr_i32 s47, s46, 31
	s_lshl_b64 s[48:49], s[46:47], 19
	s_add_u32 s48, s26, s48
	s_addc_u32 s49, s27, s49
	s_and_b64 s[50:51], s[38:39], exec
	s_cselect_b32 s47, s49, s53
	s_cselect_b32 s68, s48, s52
	s_ashr_i32 s31, s30, 31
	s_lshl_b64 s[50:51], s[30:31], 19
	s_add_u32 s50, s28, s50
	s_addc_u32 s51, s29, s51
	s_and_b64 s[56:57], s[38:39], exec
	s_cselect_b32 s31, s51, s55
	s_cselect_b32 s69, s50, s54
	s_add_u32 s70, s54, 0x100
	v_mov_b32_e32 v0, 0
	s_addc_u32 s71, s55, 0
	s_mov_b32 s72, -2
	v_mov_b32_e32 v1, v0
	v_mov_b32_e32 v2, v0
	v_mov_b32_e32 v3, v0
	v_mov_b32_e32 v4, v0
	v_mov_b32_e32 v5, v0
	v_mov_b32_e32 v6, v0
	v_mov_b32_e32 v7, v0
	v_mov_b32_e32 v16, v0
	v_mov_b32_e32 v17, v0
	v_mov_b32_e32 v18, v0
	v_mov_b32_e32 v19, v0
	v_mov_b32_e32 v20, v0
	v_mov_b32_e32 v21, v0
	v_mov_b32_e32 v22, v0
	v_mov_b32_e32 v23, v0
	v_mov_b32_e32 v32, v0
	v_mov_b32_e32 v33, v0
	v_mov_b32_e32 v34, v0
	v_mov_b32_e32 v35, v0
	v_mov_b32_e32 v36, v0
	v_mov_b32_e32 v37, v0
	v_mov_b32_e32 v38, v0
	v_mov_b32_e32 v39, v0
	v_mov_b32_e32 v48, v0
	v_mov_b32_e32 v49, v0
	v_mov_b32_e32 v50, v0
	v_mov_b32_e32 v51, v0
	v_mov_b32_e32 v52, v0
	v_mov_b32_e32 v53, v0
	v_mov_b32_e32 v54, v0
	v_mov_b32_e32 v55, v0
	v_mov_b32_e32 v8, v0
	v_mov_b32_e32 v9, v0
	v_mov_b32_e32 v10, v0
	v_mov_b32_e32 v11, v0
	v_mov_b32_e32 v12, v0
	v_mov_b32_e32 v13, v0
	v_mov_b32_e32 v14, v0
	v_mov_b32_e32 v15, v0
	v_mov_b32_e32 v24, v0
	v_mov_b32_e32 v25, v0
	v_mov_b32_e32 v26, v0
	v_mov_b32_e32 v27, v0
	v_mov_b32_e32 v28, v0
	v_mov_b32_e32 v29, v0
	v_mov_b32_e32 v30, v0
	v_mov_b32_e32 v31, v0
	v_mov_b32_e32 v40, v0
	v_mov_b32_e32 v41, v0
	v_mov_b32_e32 v42, v0
	v_mov_b32_e32 v43, v0
	v_mov_b32_e32 v44, v0
	v_mov_b32_e32 v45, v0
	v_mov_b32_e32 v46, v0
	v_mov_b32_e32 v47, v0
	v_mov_b32_e32 v56, v0
	v_mov_b32_e32 v57, v0
	v_mov_b32_e32 v58, v0
	v_mov_b32_e32 v59, v0
	v_mov_b32_e32 v60, v0
	v_mov_b32_e32 v61, v0
	v_mov_b32_e32 v62, v0
	v_mov_b32_e32 v63, v0
	v_mov_b32_e32 v66, v0
	v_mov_b32_e32 v67, v0
	v_mov_b32_e32 v68, v0
	v_mov_b32_e32 v69, v0
	v_mov_b32_e32 v70, v0
	v_mov_b32_e32 v71, v0
	v_mov_b32_e32 v72, v0
	v_mov_b32_e32 v73, v0
	v_mov_b32_e32 v82, v0
	v_mov_b32_e32 v83, v0
	v_mov_b32_e32 v84, v0
	v_mov_b32_e32 v85, v0
	v_mov_b32_e32 v86, v0
	v_mov_b32_e32 v87, v0
	v_mov_b32_e32 v88, v0
	v_mov_b32_e32 v89, v0
	v_mov_b32_e32 v98, v0
	v_mov_b32_e32 v99, v0
	v_mov_b32_e32 v100, v0
	v_mov_b32_e32 v101, v0
	v_mov_b32_e32 v102, v0
	v_mov_b32_e32 v103, v0
	v_mov_b32_e32 v104, v0
	v_mov_b32_e32 v105, v0
	v_mov_b32_e32 v114, v0
	v_mov_b32_e32 v115, v0
	v_mov_b32_e32 v116, v0
	v_mov_b32_e32 v117, v0
	v_mov_b32_e32 v118, v0
	v_mov_b32_e32 v119, v0
	v_mov_b32_e32 v120, v0
	v_mov_b32_e32 v121, v0
	v_mov_b32_e32 v74, v0
	v_mov_b32_e32 v75, v0
	v_mov_b32_e32 v76, v0
	v_mov_b32_e32 v77, v0
	v_mov_b32_e32 v78, v0
	v_mov_b32_e32 v79, v0
	v_mov_b32_e32 v80, v0
	v_mov_b32_e32 v81, v0
	v_mov_b32_e32 v90, v0
	v_mov_b32_e32 v91, v0
	v_mov_b32_e32 v92, v0
	v_mov_b32_e32 v93, v0
	v_mov_b32_e32 v94, v0
	v_mov_b32_e32 v95, v0
	v_mov_b32_e32 v96, v0
	v_mov_b32_e32 v97, v0
	v_mov_b32_e32 v106, v0
	v_mov_b32_e32 v107, v0
	v_mov_b32_e32 v108, v0
	v_mov_b32_e32 v109, v0
	v_mov_b32_e32 v110, v0
	v_mov_b32_e32 v111, v0
	v_mov_b32_e32 v112, v0
	v_mov_b32_e32 v113, v0
	v_mov_b32_e32 v122, v0
	v_mov_b32_e32 v123, v0
	v_mov_b32_e32 v124, v0
	v_mov_b32_e32 v125, v0
	v_mov_b32_e32 v126, v0
	v_mov_b32_e32 v127, v0
	v_mov_b32_e32 v128, v0
	v_mov_b32_e32 v129, v0
	s_waitcnt vmcnt(0)

.LBB0_1251:
	s_ashr_i32 s47, s46, 31
	s_lshl_b64 s[28:29], s[46:47], 19
	s_add_u32 s48, s56, s28
	s_addc_u32 s49, s57, s29
	s_and_b64 s[28:29], s[38:39], exec
	s_cselect_b32 s28, s49, s53
	s_cselect_b32 s29, s48, s52
	s_ashr_i32 s45, s44, 31
	s_lshl_b64 s[50:51], s[44:45], 19
	s_add_u32 s50, s34, s50
	s_addc_u32 s51, s58, s51
	s_and_b64 s[54:55], s[38:39], exec
	s_cselect_b32 s33, s51, s1
	s_cselect_b32 s35, s50, s0
	s_add_u32 s45, s0, 0x100
	s_addc_u32 s47, s1, 0
	s_add_u32 s0, s52, 0x40080
	v_mov_b32_e32 v0, 0
	s_addc_u32 s1, s53, 0
	s_mov_b32 s67, -2
	v_mov_b32_e32 v1, v0
	v_mov_b32_e32 v2, v0
	v_mov_b32_e32 v3, v0
	v_mov_b32_e32 v4, v0
	v_mov_b32_e32 v5, v0
	v_mov_b32_e32 v6, v0
	v_mov_b32_e32 v7, v0
	v_mov_b32_e32 v16, v0
	v_mov_b32_e32 v17, v0
	v_mov_b32_e32 v18, v0
	v_mov_b32_e32 v19, v0
	v_mov_b32_e32 v20, v0
	v_mov_b32_e32 v21, v0
	v_mov_b32_e32 v22, v0
	v_mov_b32_e32 v23, v0
	v_mov_b32_e32 v32, v0
	v_mov_b32_e32 v33, v0
	v_mov_b32_e32 v34, v0
	v_mov_b32_e32 v35, v0
	v_mov_b32_e32 v36, v0
	v_mov_b32_e32 v37, v0
	v_mov_b32_e32 v38, v0
	v_mov_b32_e32 v39, v0
	v_mov_b32_e32 v48, v0
	v_mov_b32_e32 v49, v0
	v_mov_b32_e32 v50, v0
	v_mov_b32_e32 v51, v0
	v_mov_b32_e32 v52, v0
	v_mov_b32_e32 v53, v0
	v_mov_b32_e32 v54, v0
	v_mov_b32_e32 v55, v0
	v_mov_b32_e32 v8, v0
	v_mov_b32_e32 v9, v0
	v_mov_b32_e32 v10, v0
	v_mov_b32_e32 v11, v0
	v_mov_b32_e32 v12, v0
	v_mov_b32_e32 v13, v0
	v_mov_b32_e32 v14, v0
	v_mov_b32_e32 v15, v0
	v_mov_b32_e32 v24, v0
	v_mov_b32_e32 v25, v0
	v_mov_b32_e32 v26, v0
	v_mov_b32_e32 v27, v0
	v_mov_b32_e32 v28, v0
	v_mov_b32_e32 v29, v0
	v_mov_b32_e32 v30, v0
	v_mov_b32_e32 v31, v0
	v_mov_b32_e32 v40, v0
	v_mov_b32_e32 v41, v0
	v_mov_b32_e32 v42, v0
	v_mov_b32_e32 v43, v0
	v_mov_b32_e32 v44, v0
	v_mov_b32_e32 v45, v0
	v_mov_b32_e32 v46, v0
	v_mov_b32_e32 v47, v0
	v_mov_b32_e32 v56, v0
	v_mov_b32_e32 v57, v0
	v_mov_b32_e32 v58, v0
	v_mov_b32_e32 v59, v0
	v_mov_b32_e32 v60, v0
	v_mov_b32_e32 v61, v0
	v_mov_b32_e32 v62, v0
	v_mov_b32_e32 v63, v0
	v_mov_b32_e32 v66, v0
	v_mov_b32_e32 v67, v0
	v_mov_b32_e32 v68, v0
	v_mov_b32_e32 v69, v0
	v_mov_b32_e32 v70, v0
	v_mov_b32_e32 v71, v0
	v_mov_b32_e32 v72, v0
	v_mov_b32_e32 v73, v0
	v_mov_b32_e32 v82, v0
	v_mov_b32_e32 v83, v0
	v_mov_b32_e32 v84, v0
	v_mov_b32_e32 v85, v0
	v_mov_b32_e32 v86, v0
	v_mov_b32_e32 v87, v0
	v_mov_b32_e32 v88, v0
	v_mov_b32_e32 v89, v0
	v_mov_b32_e32 v98, v0
	v_mov_b32_e32 v99, v0
	v_mov_b32_e32 v100, v0
	v_mov_b32_e32 v101, v0
	v_mov_b32_e32 v102, v0
	v_mov_b32_e32 v103, v0
	v_mov_b32_e32 v104, v0
	v_mov_b32_e32 v105, v0
	v_mov_b32_e32 v114, v0
	v_mov_b32_e32 v115, v0
	v_mov_b32_e32 v116, v0
	v_mov_b32_e32 v117, v0
	v_mov_b32_e32 v118, v0
	v_mov_b32_e32 v119, v0
	v_mov_b32_e32 v120, v0
	v_mov_b32_e32 v121, v0
	v_mov_b32_e32 v74, v0
	v_mov_b32_e32 v75, v0
	v_mov_b32_e32 v76, v0
	v_mov_b32_e32 v77, v0
	v_mov_b32_e32 v78, v0
	v_mov_b32_e32 v79, v0
	v_mov_b32_e32 v80, v0
	v_mov_b32_e32 v81, v0
	v_mov_b32_e32 v90, v0
	v_mov_b32_e32 v91, v0
	v_mov_b32_e32 v92, v0
	v_mov_b32_e32 v93, v0
	v_mov_b32_e32 v94, v0
	v_mov_b32_e32 v95, v0
	v_mov_b32_e32 v96, v0
	v_mov_b32_e32 v97, v0
	v_mov_b32_e32 v106, v0
	v_mov_b32_e32 v107, v0
	v_mov_b32_e32 v108, v0
	v_mov_b32_e32 v109, v0
	v_mov_b32_e32 v110, v0
	v_mov_b32_e32 v111, v0
	v_mov_b32_e32 v112, v0
	v_mov_b32_e32 v113, v0
	v_mov_b32_e32 v122, v0
	v_mov_b32_e32 v123, v0
	v_mov_b32_e32 v124, v0
	v_mov_b32_e32 v125, v0
	v_mov_b32_e32 v126, v0
	v_mov_b32_e32 v127, v0
	v_mov_b32_e32 v128, v0
	v_mov_b32_e32 v129, v0
	s_waitcnt vmcnt(0)
